# phase 0 converts exactly one weight block per wave (items <2048, all the in-projection needs); the 80 remaining gate-column blocks join the idle-slot pass
# speedup vs baseline: 1.0106x; 1.0009x over previous
; #define LAS __attribute__((address_space(3)))
; __device__ __forceinline__ void wprep_phase(const WArgs& a, LAS float* scr, int gw, int NGW, int lane, int gtid, int NGT) {
;     constexpr int I0 = 16 * 133, I1 = 6 * 24, I2 = 4 * 32, I3 = 8 * 32, I4 = 4 * 32, I5 = 16 * 32, I6 = 16 * 128, I7 = 64 * 32;
;     constexpr int NIT = I0 + I1 + I2 + I3 + I4 + I5 + I6 + I7;
;     for (int it = gw; it < NIT; it += NGW) {
;         int r = it;
;         if (r < I0) { const int kb = r / 133, nb = r % 133; tr_item(a.w_in, IN_COLS, 64 * kb, 32 * nb, a.W + WO_IN, 1024, win_dst(32 * nb), scr, lane, a.g_mix); continue; } r -= I0;
.Lwp_e1:
	s_ashr_i32 s77, s76, 31
	s_ashr_i32 s31, s30, 31
	s_cmpk_gt_i32 s34, 0x1cdf
	v_and_b32_e32 v80, 63, v81
	s_cbranch_scc1 .LBB0_698
	s_lshl_b32 s0, s76, 10
	s_ashr_i32 s1, s0, 31
	s_mov_b64 s[4:5], s[80:81]
	v_readlane_b32 s80, v253, 0
	s_lshl_b64 s[0:1], s[0:1], 2
	v_readlane_b32 s81, v253, 1
	v_readlane_b32 s82, v253, 2
	v_readlane_b32 s83, v253, 3
	s_mov_b64 s[80:81], s[4:5]
	s_add_u32 s36, s82, s0
	v_readlane_b32 s4, v253, 32
	s_addc_u32 s37, s83, s1
	v_readlane_b32 s14, v253, 42
	v_readlane_b32 s15, v253, 43
	s_add_u32 s40, s14, s0
	s_mul_i32 s0, s76, 0x180
	s_addc_u32 s41, s15, s1
	s_ashr_i32 s1, s0, 31
	v_readlane_b32 s92, v253, 12
	s_lshl_b64 s[0:1], s[0:1], 2
	v_readlane_b32 s93, v253, 13
	v_readlane_b32 s5, v253, 33
	s_add_u32 s42, s92, s0
	s_addc_u32 s43, s93, s1
	s_lshl_b64 s[0:1], s[30:31], 2
	s_mov_b64 s[4:5], s[76:77]
	v_readlane_b32 s64, v253, 16
	v_readlane_b32 s65, v253, 17
	s_add_u32 s52, s64, s0
	v_readlane_b32 s18, v253, 46
	v_readlane_b32 s76, v253, 28
	v_readlane_b32 s77, v253, 29
	s_addc_u32 s53, s65, s1
	s_lshl_b64 s[0:1], s[4:5], 24
	v_readlane_b32 s19, v253, 47
	s_mov_b64 s[76:77], s[4:5]
	s_add_u32 s4, s18, s0
	v_readlane_b32 s16, v253, 44
	s_addc_u32 s5, s19, s1
	v_readlane_b32 s17, v253, 45
	s_add_u32 s0, s16, s0
	v_readlane_b32 s12, v253, 40
	s_addc_u32 s1, s17, s1
	s_lshl_b64 s[20:21], s[76:77], 22
	v_readlane_b32 s13, v253, 41
	s_add_u32 s20, s12, s20
	v_readlane_b32 s8, v253, 36
	s_addc_u32 s21, s13, s21
	s_lshl_b64 s[38:39], s[76:77], 20
	v_readlane_b32 s9, v253, 37
	s_add_u32 s44, s8, s38
	v_readlane_b32 s68, v253, 20
	s_addc_u32 s45, s9, s39
	s_lshl_b64 s[46:47], s[76:77], 21
	v_readlane_b32 s69, v253, 21
	s_add_u32 s46, s68, s46
	v_readlane_b32 s66, v253, 18
	s_addc_u32 s47, s69, s47
	v_lshlrev_b32_e32 v0, 4, v80
	v_readlane_b32 s67, v253, 19
	s_add_u32 s38, s66, s38
	v_and_b32_e32 v0, 0x70, v0
	v_readlane_b32 s94, v253, 14
	s_addc_u32 s39, s67, s39
	s_waitcnt vmcnt(0) lgkmcnt(0)
	v_lshl_add_u64 v[40:41], s[0:1], 0, v[0:1]
	s_mul_i32 s0, s76, 0x120000
	v_readlane_b32 s95, v253, 15
	s_mul_hi_i32 s15, s76, 0x120000
	s_add_u32 s0, s94, s0
	v_readlane_b32 s84, v253, 4
	s_addc_u32 s1, s95, s15
	s_mul_i32 s16, s76, 0x10a0000
	v_readlane_b32 s85, v253, 5
	s_mul_hi_i32 s15, s76, 0x10a0000
	s_add_u32 s16, s84, s16
	v_lshlrev_b32_e32 v2, 3, v80
	s_addc_u32 s17, s85, s15
	s_lshl_b32 s15, s54, 14
	v_lshrrev_b32_e32 v44, 3, v80
	v_and_b32_e32 v2, 56, v2
	s_add_i32 s15, s15, 0
	v_mul_u32_u24_e32 v3, 0x84, v2
	v_lshlrev_b32_e32 v4, 2, v44
	v_lshl_add_u64 v[38:39], s[4:5], 0, v[0:1]
	v_lshl_add_u64 v[42:43], s[20:21], 0, v[0:1]
	v_add_u32_e32 v82, s15, v0
	v_add3_u32 v87, s15, v3, v4
	v_or_b32_e32 v3, 32, v44
	v_lshl_add_u64 v[46:47], s[44:45], 0, v[0:1]
	v_lshl_add_u64 v[48:49], s[46:47], 0, v[0:1]
	v_lshl_add_u64 v[50:51], s[38:39], 0, v[0:1]
	v_lshl_add_u64 v[52:53], s[0:1], 0, v[0:1]
	v_lshl_add_u64 v[54:55], s[16:17], 0, v[0:1]
	v_lshlrev_b32_e32 v0, 1, v2
	v_mul_u32_u24_e32 v88, 0x84, v3
	v_lshl_add_u64 v[2:3], s[50:51], 0, v[0:1]
	s_mov_b64 s[0:1], 0x17d0000
	v_lshl_add_u64 v[58:59], v[2:3], 0, s[0:1]
	s_mov_b64 s[0:1], 0xfd0000
	v_lshl_add_u64 v[60:61], v[2:3], 0, s[0:1]
	s_mov_b64 s[0:1], 0xdd0000
	v_lshl_add_u64 v[62:63], v[2:3], 0, s[0:1]
	s_mov_b64 s[0:1], 0xbd0600
	v_lshl_add_u64 v[64:65], v[2:3], 0, s[0:1]
	s_mov_b64 s[0:1], 0xbd0200
	v_lshl_add_u64 v[66:67], v[2:3], 0, s[0:1]
	s_mov_b64 s[0:1], 0xb50000
	v_readlane_b32 s78, v253, 30
	v_readlane_b32 s79, v253, 31
	v_lshl_add_u64 v[68:69], v[2:3], 0, s[0:1]
	s_mov_b64 s[0:1], 0xb10000
	v_readlane_b32 s70, v253, 22
	v_readlane_b32 s71, v253, 23
	v_readlane_b32 s73, v253, 25
	v_readlane_b32 s75, v253, 27
	v_readlane_b32 s78, v254, 58
	v_readlane_b32 s94, v255, 0
	v_lshl_add_u64 v[70:71], v[2:3], 0, s[0:1]
	s_mov_b64 s[0:1], 0xa80000
	s_movk_i32 s83, 0x600
	s_mov_b32 s71, 0x30000
	s_movk_i32 s75, 0x5000
	s_movk_i32 s73, 0x60
	s_movk_i32 s70, 0x6000
	v_readlane_b32 s79, v254, 59
	s_movk_i32 s64, 0x2000
	s_movk_i32 s65, 0xd0
	s_mov_b32 s63, 0x2aaaaaab
	s_movk_i32 s66, 0x4000
	v_mul_u32_u24_e32 v83, 0x84, v44
	v_or_b32_e32 v84, 8, v44
	v_or_b32_e32 v85, 16, v44
	v_or_b32_e32 v86, 24, v44
	v_lshl_add_u64 v[56:57], s[24:25], 0, v[0:1]
	v_lshl_add_u64 v[72:73], v[2:3], 0, s[0:1]
	v_mov_b32_e32 v45, v1
	v_readlane_b32 s0, v255, 12
	s_cmp_eq_u32 s0, 1
	s_cbranch_scc0 .Lwp_norm
	s_add_i32 s34, s34, 0x400
	s_lshr_b32 s94, s94, 1

; __device__ __forceinline__ void wprep_phase(const WArgs& a, LAS float* scr, int gw, int NGW, int lane, int gtid, int NGT) {
;     ...
;     for (int it = gw; it < NIT; it += NGW) {
;         int r = it;
.LBB0_573:
	s_add_i32 s46, s46, s94
	s_add_i32 s15, s15, s16
	s_add_i32 s17, s17, s19
	s_add_i32 s44, s44, s45
	s_cmpk_gt_i32 s46, 0x1cdf
	s_cbranch_scc1 .LBB0_698
	s_cmpk_lt_i32 s46, 0x800
	s_cbranch_scc1 .LBB0_574
	v_readlane_b32 s0, v255, 12
	s_cmp_eq_u32 s0, 2
	s_cbranch_scc1 .LBB0_698

; __device__ __forceinline__ void wprep_phase(const WArgs& a, LAS float* scr, int gw, int NGW, int lane, int gtid, int NGT) {
;     ...
;     for (int e = gtid; e < 256; e += NGT) a.cdec[e] = -8.0f * log1pf(expf(-a.lam[e]));
.LBB0_698:
	v_readlane_b32 s0, v255, 12
	s_cmp_eq_u32 s0, 1
	s_cbranch_scc0 .Lwp_x
	s_sub_i32 s34, s34, 0x400
